# in-proj epilogue, rotary tiles: rope-table loads of step s issued in step s-1 before its streaming stores (wait vmcnt(2) instead of vmcnt(0) behind the stores)
# speedup vs baseline: 1.0167x; 1.0067x over previous
;   DI void operator()(g8::Acc& acc, int pm, int pn, int wr, int wc, int fr, int fq) const {
;     ...
;           if (seg < 2) {
;             if (bj == 0) {
;               const f32x4 c0 = gld<f32x4>(rope, (unsigned)row * 64u), c1 = gld<f32x4>(rope, (unsigned)row * 64u + 16u), s0 = gld<f32x4>(rope, (unsigned)row * 64u + 32u) * sgn, s1 = gld<f32x4>(rope, (unsigned)row * 64u + 48u) * sgn;
;               f32x4 p0, p1;
; #pragma unroll
;               for (int e = 0; e < 4; ++e) { p0[e] = __shfl_xor(o0[e], 16); p1[e] = __shfl_xor(o1[e], 16); }
;               const f32x4 r0 = o0 * c0 + p0 * s0, r1 = o1 * c1 + p1 * s1;
; #pragma unroll
;               for (int e = 0; e < 4; ++e) { o0[e] = use ? r0[e] : o0[e]; o1[e] = use ? r1[e] : o1[e]; }
;             }
;             o0 = o0 * qs; o1 = o1 * qs;
.LBB0_168:
	v_cndmask_b32_e64 v144, 1.0, v164, s[8:9]
	s_lshl_b32 s18, s10, 8
	s_add_i32 s18, s18, s93
	v_or_b32_e32 v249, s18, v155
	v_lshlrev_b32_e32 v249, 6, v249
	s_andn2_b64 vcc, exec, s[0:1]
	v_mov_b32_e32 v145, v144
	s_cbranch_vccnz .LBB0_170
	v_or_b32_e32 v146, s18, v155
	v_lshlrev_b32_e32 v170, 6, v146
	global_load_dwordx4 v[146:149], v170, s[74:75] offset:16
	global_load_dwordx4 v[150:153], v170, s[74:75] offset:48
	global_load_dwordx4 v[166:169], v170, s[74:75]
	s_nop 0
	global_load_dwordx4 v[170:173], v170, s[74:75] offset:32
	v_and_b32_e32 v175, 64, v165
	v_xor_b32_e32 v174, 16, v165
	v_add_u32_e32 v175, 64, v175
	v_cmp_lt_i32_e32 vcc, v174, v175
	s_waitcnt vmcnt(0)
	v_pk_mul_f32 v[152:153], v[138:139], v[152:153]
	v_cndmask_b32_e32 v174, v165, v174, vcc
	v_lshlrev_b32_e32 v181, 2, v174
	ds_bpermute_b32 v174, v181, v124
	ds_bpermute_b32 v176, v181, v120
	ds_bpermute_b32 v175, v181, v125
	ds_bpermute_b32 v177, v181, v121
	ds_bpermute_b32 v178, v181, v126
	ds_bpermute_b32 v180, v181, v122
	ds_bpermute_b32 v179, v181, v127
	ds_bpermute_b32 v181, v181, v123
	v_pk_mul_f32 v[172:173], v[138:139], v[172:173]
	v_pk_mul_f32 v[170:171], v[136:137], v[170:171]
	v_pk_mul_f32 v[150:151], v[136:137], v[150:151]
	s_waitcnt lgkmcnt(5)
	v_pk_mul_f32 v[170:171], v[170:171], v[174:175]
	s_waitcnt lgkmcnt(1)
	v_pk_mul_f32 v[172:173], v[172:173], v[178:179]
	v_pk_mul_f32 v[150:151], v[150:151], v[176:177]
	s_waitcnt lgkmcnt(0)
	v_pk_mul_f32 v[152:153], v[152:153], v[180:181]
	v_pk_fma_f32 v[168:169], v[126:127], v[168:169], v[172:173]
	v_pk_fma_f32 v[166:167], v[124:125], v[166:167], v[170:171]
	v_pk_fma_f32 v[148:149], v[122:123], v[148:149], v[152:153]
	v_pk_fma_f32 v[146:147], v[120:121], v[146:147], v[150:151]
	v_cndmask_b32_e64 v125, v125, v167, s[4:5]
	v_cndmask_b32_e64 v124, v124, v166, s[4:5]
	v_cndmask_b32_e64 v127, v127, v169, s[4:5]
	v_cndmask_b32_e64 v126, v126, v168, s[4:5]
	v_cndmask_b32_e64 v121, v121, v147, s[4:5]
	v_cndmask_b32_e64 v120, v120, v146, s[4:5]
	v_cndmask_b32_e64 v123, v123, v149, s[4:5]
	v_cndmask_b32_e64 v122, v122, v148, s[4:5]
	v_mov_b32_e32 v150, v144
	v_mov_b32_e32 v151, v144
	v_pk_mul_f32 v[148:149], v[150:151], v[126:127]
	v_pk_mul_f32 v[146:147], v[144:145], v[124:125]
	v_pk_mul_f32 v[152:153], v[150:151], v[122:123]
	v_pk_mul_f32 v[150:151], v[144:145], v[120:121]

;   DI void operator()(g8::Acc& acc, int pm, int pn, int wr, int wc, int fr, int fq) const {
;     ...
;     if (seg < 5) { dst = slot(p, seg + 1); ld = 1024; cofs = seg * 1024; } else { dst = (bf16_t*)p.out; ld = 2048; cofs = 5 * 1024; }
;     const float qs = (seg == 0) ? 0.125f * LOG2E : 1.0f;
;     const float sgn = (fq == 0) ? -1.0f : 1.0f; const bool use = fq < 2;
;     const unsigned col0 = (unsigned)(pn * BM + wc * 64 - cofs);
; #pragma unroll
;     for (int ai = 0; ai < 2; ++ai)
; #pragma unroll
;       for (int m = 0; m < 4; ++m) {
;         const int row0 = pm * BM + ai * HALF + wr * 64 + m * 16, row = row0 + fr;
;         u32x4 w[2];
; #pragma unroll
;         for (int bj = 0; bj < 2; ++bj) {
;           f32x4 o0 = acc[ai][bj][m][0], o1 = acc[ai][bj][m][1];
;           if (seg < 2) {
;             if (bj == 0) {
;               const f32x4 c0 = gld<f32x4>(rope, (unsigned)row * 64u), c1 = gld<f32x4>(rope, (unsigned)row * 64u + 16u), s0 = gld<f32x4>(rope, (unsigned)row * 64u + 32u) * sgn, s1 = gld<f32x4>(rope, (unsigned)row * 64u + 48u) * sgn;
;               f32x4 p0, p1;
; #pragma unroll
;               for (int e = 0; e < 4; ++e) { p0[e] = __shfl_xor(o0[e], 16); p1[e] = __shfl_xor(o1[e], 16); }
;               const f32x4 r0 = o0 * c0 + p0 * s0, r1 = o1 * c1 + p1 * s1;
; #pragma unroll
;               for (int e = 0; e < 4; ++e) { o0[e] = use ? r0[e] : o0[e]; o1[e] = use ? r1[e] : o1[e]; }
;             }
;             o0 = o0 * qs; o1 = o1 * qs;
;           } else if (seg == 3 || seg == 4) {
; #pragma unroll
;             for (int e = 0; e < 4; ++e) {
;               { const float xx = o0[e], y2 = (-2.0f * 0.7978845608028654f * LOG2E) * (xx + 0.044715f * xx * xx * xx); o0[e] = xx * __builtin_amdgcn_rcpf(1.0f + __builtin_amdgcn_exp2f(y2)); }
;               { const float xx = o1[e], y2 = (-2.0f * 0.7978845608028654f * LOG2E) * (xx + 0.044715f * xx * xx * xx); o1[e] = xx * __builtin_amdgcn_rcpf(1.0f + __builtin_amdgcn_exp2f(y2)); }
;             }
;           } else if (seg >= 5) {
; #pragma unroll
;             for (int e = 0; e < 4; ++e) { o0[e] = __builtin_amdgcn_rcpf(1.0f + __builtin_amdgcn_exp2f(-LOG2E * o0[e])); o1[e] = __builtin_amdgcn_rcpf(1.0f + __builtin_amdgcn_exp2f(-LOG2E * o1[e])); }
;           }
;           w[bj] = pk8(o0, o1);
;         }
;         st_rows16<true>(dst, ld * 2u, (unsigned)row0, col0, fr, fq, w[0], w[1]);
.LBB0_180:
	s_cmp_lt_i32 s90, 5
	s_cselect_b64 s[0:1], -1, 0
	s_ashr_i32 s91, s90, 31
	s_lshl_b64 s[20:21], s[90:91], 26
	s_add_u32 s19, s44, s20
	s_addc_u32 s20, s45, s21
	s_add_u32 s19, s19, 0x4000000
	s_addc_u32 s22, s20, 0
	s_min_i32 s23, s90, 5
	s_and_b64 s[20:21], s[0:1], exec
	s_cselect_b32 s91, s22, s73
	s_cselect_b32 s90, s19, s72
	s_lshl_b32 s19, s92, 8
	s_or_b32 s19, s19, s77
	s_lshl_b32 s20, s23, 10
	s_sub_i32 s19, s19, s20
	v_or_b32_e32 v112, s19, v156
	v_or_b32_e32 v116, v112, v159
	v_or_b32_e32 v112, v112, v160
	v_cvt_pk_bf16_f32 v113, v146, v147
	v_lshlrev_b32_e32 v146, 1, v112
	v_cvt_pk_bf16_f32 v112, v120, v121
	v_mov_b32_e32 v120, 0
	s_and_b64 s[0:1], s[0:1], exec
	v_lshlrev_b32_e32 v147, 1, v116
	v_cvt_pk_bf16_f32 v116, v122, v123
	v_cvt_pk_bf16_f32 v117, v124, v125
	v_cvt_pk_bf16_f32 v118, v126, v127
	v_mov_b32_dpp v120, v112 row_ror:8 row_mask:0xf bank_mask:0xf
	v_mov_b32_e32 v121, 0
	v_mov_b32_e32 v122, 0
	v_mov_b32_e32 v123, 0
	v_cvt_pk_bf16_f32 v114, v148, v149
	v_cvt_pk_bf16_f32 v115, v150, v151
	v_cvt_pk_bf16_f32 v119, v152, v153
	s_cselect_b32 s19, 11, 12
	v_mov_b32_dpp v121, v116 row_ror:8 row_mask:0xf bank_mask:0xf
	v_mov_b32_dpp v122, v117 row_ror:8 row_mask:0xf bank_mask:0xf
	v_mov_b32_dpp v123, v118 row_ror:8 row_mask:0xf bank_mask:0xf
	v_cndmask_b32_e64 v112, v113, v120, s[6:7]
	v_cndmask_b32_e64 v116, v120, v113, s[6:7]
	v_or_b32_e32 v120, s18, v158
	v_cndmask_b32_e64 v113, v114, v121, s[6:7]
	v_cndmask_b32_e64 v117, v121, v114, s[6:7]
	v_cndmask_b32_e64 v114, v115, v122, s[6:7]
	v_cndmask_b32_e64 v118, v122, v115, s[6:7]
	v_cndmask_b32_e64 v115, v119, v123, s[6:7]
	v_lshl_add_u32 v121, v120, s19, v147
	s_and_b64 vcc, exec, s[10:11]
	s_cbranch_vccz .Lrope_pf_skip1
	v_add_u32_e32 v248, 0x400, v249
	global_load_dwordx4 v[232:235], v248, s[74:75] offset:16
	global_load_dwordx4 v[236:239], v248, s[74:75] offset:48
	global_load_dwordx4 v[240:243], v248, s[74:75]
	global_load_dwordx4 v[244:247], v248, s[74:75] offset:32
.Lrope_pf_skip1:
	global_store_dwordx4 v121, v[112:115], s[90:91] nt
	v_cndmask_b32_e64 v119, v123, v119, s[6:7]
	s_and_b64 vcc, exec, s[10:11]
	v_or_b32_e32 v112, 8, v120
	v_lshl_add_u32 v112, v112, s19, v146
	s_mov_b64 s[0:1], -1
	global_store_dwordx4 v112, v[116:119], s[90:91] nt
	s_cbranch_vccnz .LBB0_188
	s_and_b64 vcc, exec, s[8:9]
	s_cbranch_vccnz .LBB0_185
	s_andn2_b64 vcc, exec, s[88:89]
	v_mov_b32_e32 v115, v111
	v_mov_b32_e32 v114, v110
	v_mov_b32_e32 v113, v109
	v_mov_b32_e32 v112, v108
	v_mov_b32_e32 v119, v107
	v_mov_b32_e32 v118, v106
	v_mov_b32_e32 v117, v105
	v_mov_b32_e32 v116, v104
	s_cbranch_vccnz .LBB0_184
	v_mul_f32_e32 v113, 0xbfb8aa3b, v104
	v_exp_f32_e32 v113, v113
	v_mul_f32_e32 v114, 0xbfb8aa3b, v109
	v_mul_f32_e32 v115, 0xbfb8aa3b, v105
	v_exp_f32_e32 v114, v114
	v_exp_f32_e32 v115, v115
	v_add_f32_e32 v113, 1.0, v113
	v_rcp_f32_e32 v116, v113
	v_add_f32_e32 v113, 1.0, v114
	v_add_f32_e32 v114, 1.0, v115
	v_mul_f32_e32 v115, 0xbfb8aa3b, v110
	v_mul_f32_e32 v117, 0xbfb8aa3b, v106
	v_exp_f32_e32 v115, v115
	v_exp_f32_e32 v118, v117
	v_rcp_f32_e32 v117, v114
	v_mul_f32_e32 v112, 0xbfb8aa3b, v108
	v_add_f32_e32 v114, 1.0, v115
	v_add_f32_e32 v115, 1.0, v118
	v_mul_f32_e32 v118, 0xbfb8aa3b, v111
	v_exp_f32_e32 v119, v118
	v_mul_f32_e32 v118, 0xbfb8aa3b, v107
	v_exp_f32_e32 v112, v112
	v_exp_f32_e32 v120, v118
	v_rcp_f32_e32 v118, v115
	v_add_f32_e32 v115, 1.0, v119
	v_add_f32_e32 v112, 1.0, v112
	v_add_f32_e32 v119, 1.0, v120
	v_rcp_f32_e32 v112, v112
	v_rcp_f32_e32 v113, v113
	v_rcp_f32_e32 v114, v114
	v_rcp_f32_e32 v115, v115
	v_rcp_f32_e32 v119, v119

;   DI void operator()(g8::Acc& acc, int pm, int pn, int wr, int wc, int fr, int fq) const {
;     ...
;           if (seg < 2) {
;             if (bj == 0) {
;               const f32x4 c0 = gld<f32x4>(rope, (unsigned)row * 64u), c1 = gld<f32x4>(rope, (unsigned)row * 64u + 16u), s0 = gld<f32x4>(rope, (unsigned)row * 64u + 32u) * sgn, s1 = gld<f32x4>(rope, (unsigned)row * 64u + 48u) * sgn;
;               f32x4 p0, p1;
; #pragma unroll
;               for (int e = 0; e < 4; ++e) { p0[e] = __shfl_xor(o0[e], 16); p1[e] = __shfl_xor(o1[e], 16); }
;               const f32x4 r0 = o0 * c0 + p0 * s0, r1 = o1 * c1 + p1 * s1;
; #pragma unroll
;               for (int e = 0; e < 4; ++e) { o0[e] = use ? r0[e] : o0[e]; o1[e] = use ? r1[e] : o1[e]; }
;             }
;             o0 = o0 * qs; o1 = o1 * qs;
.LBB0_189:
	v_and_b32_e32 v149, 64, v165
	v_xor_b32_e32 v148, 16, v165
	v_add_u32_e32 v149, 64, v149
	v_cmp_lt_i32_e32 vcc, v148, v149
	s_waitcnt vmcnt(2)
	v_pk_mul_f32 v[118:119], v[138:139], v[238:239]
	v_cndmask_b32_e32 v148, v165, v148, vcc
	v_lshlrev_b32_e32 v167, 2, v148
	ds_bpermute_b32 v148, v167, v108
	ds_bpermute_b32 v150, v167, v104
	ds_bpermute_b32 v149, v167, v109
	ds_bpermute_b32 v151, v167, v105
	ds_bpermute_b32 v152, v167, v110
	ds_bpermute_b32 v166, v167, v106
	ds_bpermute_b32 v153, v167, v111
	ds_bpermute_b32 v167, v167, v107
	v_pk_mul_f32 v[126:127], v[138:139], v[246:247]
	v_pk_mul_f32 v[124:125], v[136:137], v[244:245]
	v_pk_mul_f32 v[116:117], v[136:137], v[236:237]
	s_waitcnt lgkmcnt(5)
	v_pk_mul_f32 v[124:125], v[124:125], v[148:149]
	s_waitcnt lgkmcnt(1)
	v_pk_mul_f32 v[126:127], v[126:127], v[152:153]
	v_pk_mul_f32 v[116:117], v[116:117], v[150:151]
	s_waitcnt lgkmcnt(0)
	v_pk_mul_f32 v[118:119], v[118:119], v[166:167]
	v_pk_fma_f32 v[122:123], v[110:111], v[242:243], v[126:127]
	v_pk_fma_f32 v[120:121], v[108:109], v[240:241], v[124:125]
	v_pk_fma_f32 v[114:115], v[106:107], v[234:235], v[118:119]
	v_pk_fma_f32 v[112:113], v[104:105], v[232:233], v[116:117]
	v_cndmask_b32_e64 v109, v109, v121, s[4:5]
	v_cndmask_b32_e64 v108, v108, v120, s[4:5]
	v_cndmask_b32_e64 v111, v111, v123, s[4:5]
	v_cndmask_b32_e64 v110, v110, v122, s[4:5]
	v_cndmask_b32_e64 v105, v105, v113, s[4:5]
	v_cndmask_b32_e64 v104, v104, v112, s[4:5]
	v_cndmask_b32_e64 v107, v107, v115, s[4:5]
	v_cndmask_b32_e64 v106, v106, v114, s[4:5]
	v_mov_b32_e32 v116, v144
	v_mov_b32_e32 v117, v144
	v_pk_mul_f32 v[114:115], v[116:117], v[110:111]
	v_pk_mul_f32 v[112:113], v[144:145], v[108:109]
	v_pk_mul_f32 v[118:119], v[116:117], v[106:107]
	v_pk_mul_f32 v[116:117], v[144:145], v[104:105]

;   DI void operator()(g8::Acc& acc, int pm, int pn, int wr, int wc, int fr, int fq) const {
;     ...
;     if (seg < 5) { dst = slot(p, seg + 1); ld = 1024; cofs = seg * 1024; } else { dst = (bf16_t*)p.out; ld = 2048; cofs = 5 * 1024; }
;     const float qs = (seg == 0) ? 0.125f * LOG2E : 1.0f;
;     const float sgn = (fq == 0) ? -1.0f : 1.0f; const bool use = fq < 2;
;     const unsigned col0 = (unsigned)(pn * BM + wc * 64 - cofs);
; #pragma unroll
;     for (int ai = 0; ai < 2; ++ai)
; #pragma unroll
;       for (int m = 0; m < 4; ++m) {
;         const int row0 = pm * BM + ai * HALF + wr * 64 + m * 16, row = row0 + fr;
;         u32x4 w[2];
; #pragma unroll
;         for (int bj = 0; bj < 2; ++bj) {
;           f32x4 o0 = acc[ai][bj][m][0], o1 = acc[ai][bj][m][1];
;           if (seg < 2) {
;             if (bj == 0) {
;               const f32x4 c0 = gld<f32x4>(rope, (unsigned)row * 64u), c1 = gld<f32x4>(rope, (unsigned)row * 64u + 16u), s0 = gld<f32x4>(rope, (unsigned)row * 64u + 32u) * sgn, s1 = gld<f32x4>(rope, (unsigned)row * 64u + 48u) * sgn;
;               f32x4 p0, p1;
; #pragma unroll
;               for (int e = 0; e < 4; ++e) { p0[e] = __shfl_xor(o0[e], 16); p1[e] = __shfl_xor(o1[e], 16); }
;               const f32x4 r0 = o0 * c0 + p0 * s0, r1 = o1 * c1 + p1 * s1;
; #pragma unroll
;               for (int e = 0; e < 4; ++e) { o0[e] = use ? r0[e] : o0[e]; o1[e] = use ? r1[e] : o1[e]; }
;             }
;             o0 = o0 * qs; o1 = o1 * qs;
;           } else if (seg == 3 || seg == 4) {
; #pragma unroll
;             for (int e = 0; e < 4; ++e) {
;               { const float xx = o0[e], y2 = (-2.0f * 0.7978845608028654f * LOG2E) * (xx + 0.044715f * xx * xx * xx); o0[e] = xx * __builtin_amdgcn_rcpf(1.0f + __builtin_amdgcn_exp2f(y2)); }
;               { const float xx = o1[e], y2 = (-2.0f * 0.7978845608028654f * LOG2E) * (xx + 0.044715f * xx * xx * xx); o1[e] = xx * __builtin_amdgcn_rcpf(1.0f + __builtin_amdgcn_exp2f(y2)); }
;             }
;           } else if (seg >= 5) {
; #pragma unroll
;             for (int e = 0; e < 4; ++e) { o0[e] = __builtin_amdgcn_rcpf(1.0f + __builtin_amdgcn_exp2f(-LOG2E * o0[e])); o1[e] = __builtin_amdgcn_rcpf(1.0f + __builtin_amdgcn_exp2f(-LOG2E * o1[e])); }
;           }
;           w[bj] = pk8(o0, o1);
;         }
;         st_rows16<true>(dst, ld * 2u, (unsigned)row0, col0, fr, fq, w[0], w[1]);
.LBB0_200:
	v_cvt_pk_bf16_f32 v96, v104, v105
	v_mov_b32_e32 v104, 0
	v_cvt_pk_bf16_f32 v97, v112, v113
	v_cvt_pk_bf16_f32 v100, v106, v107
	v_cvt_pk_bf16_f32 v101, v108, v109
	v_cvt_pk_bf16_f32 v102, v110, v111
	v_mov_b32_dpp v104, v96 row_ror:8 row_mask:0xf bank_mask:0xf
	v_mov_b32_e32 v105, 0
	v_mov_b32_e32 v106, 0
	v_mov_b32_e32 v107, 0
	v_cvt_pk_bf16_f32 v98, v114, v115
	v_cvt_pk_bf16_f32 v99, v116, v117
	v_cvt_pk_bf16_f32 v103, v118, v119
	v_mov_b32_dpp v105, v100 row_ror:8 row_mask:0xf bank_mask:0xf
	v_mov_b32_dpp v106, v101 row_ror:8 row_mask:0xf bank_mask:0xf
	v_mov_b32_dpp v107, v102 row_ror:8 row_mask:0xf bank_mask:0xf
	v_cndmask_b32_e64 v96, v97, v104, s[6:7]
	v_cndmask_b32_e64 v100, v104, v97, s[6:7]
	v_or_b32_e32 v104, s20, v158
	v_cndmask_b32_e64 v97, v98, v105, s[6:7]
	v_cndmask_b32_e64 v101, v105, v98, s[6:7]
	v_cndmask_b32_e64 v98, v99, v106, s[6:7]
	v_cndmask_b32_e64 v102, v106, v99, s[6:7]
	v_cndmask_b32_e64 v99, v103, v107, s[6:7]
	v_lshl_add_u32 v105, v104, s19, v147
	s_and_b64 vcc, exec, s[10:11]
	s_cbranch_vccz .Lrope_pf_skip2
	v_add_u32_e32 v248, 0x800, v249
	global_load_dwordx4 v[232:235], v248, s[74:75] offset:16
	global_load_dwordx4 v[236:239], v248, s[74:75] offset:48
	global_load_dwordx4 v[240:243], v248, s[74:75]
	global_load_dwordx4 v[244:247], v248, s[74:75] offset:32
.Lrope_pf_skip2:
	global_store_dwordx4 v105, v[96:99], s[90:91] nt
	v_cndmask_b32_e64 v103, v107, v103, s[6:7]
	s_and_b64 vcc, exec, s[10:11]
	v_or_b32_e32 v96, 8, v104
	v_lshl_add_u32 v96, v96, s19, v146
	s_mov_b64 s[0:1], -1
	global_store_dwordx4 v96, v[100:103], s[90:91] nt
	s_cbranch_vccnz .LBB0_208
	s_and_b64 vcc, exec, s[8:9]
	s_cbranch_vccnz .LBB0_205
	s_andn2_b64 vcc, exec, s[88:89]
	v_mov_b32_e32 v99, v95
	v_mov_b32_e32 v98, v94
	v_mov_b32_e32 v97, v93
	v_mov_b32_e32 v96, v92
	v_mov_b32_e32 v103, v91
	v_mov_b32_e32 v102, v90
	v_mov_b32_e32 v101, v89
	v_mov_b32_e32 v100, v88
	s_cbranch_vccnz .LBB0_204
	v_mul_f32_e32 v97, 0xbfb8aa3b, v88
	v_exp_f32_e32 v97, v97
	v_mul_f32_e32 v98, 0xbfb8aa3b, v93
	v_mul_f32_e32 v99, 0xbfb8aa3b, v89
	v_exp_f32_e32 v98, v98
	v_exp_f32_e32 v99, v99
	v_add_f32_e32 v97, 1.0, v97
	v_rcp_f32_e32 v100, v97
	v_add_f32_e32 v97, 1.0, v98
	v_add_f32_e32 v98, 1.0, v99
	v_mul_f32_e32 v99, 0xbfb8aa3b, v94
	v_mul_f32_e32 v101, 0xbfb8aa3b, v90
	v_exp_f32_e32 v99, v99
	v_exp_f32_e32 v102, v101
	v_rcp_f32_e32 v101, v98
	v_mul_f32_e32 v96, 0xbfb8aa3b, v92
	v_add_f32_e32 v98, 1.0, v99
	v_add_f32_e32 v99, 1.0, v102
	v_mul_f32_e32 v102, 0xbfb8aa3b, v95
	v_exp_f32_e32 v103, v102
	v_mul_f32_e32 v102, 0xbfb8aa3b, v91
	v_exp_f32_e32 v96, v96
	v_exp_f32_e32 v104, v102
	v_rcp_f32_e32 v102, v99
	v_add_f32_e32 v99, 1.0, v103
	v_add_f32_e32 v96, 1.0, v96
	v_add_f32_e32 v103, 1.0, v104
	v_rcp_f32_e32 v96, v96
	v_rcp_f32_e32 v97, v97
	v_rcp_f32_e32 v98, v98
	v_rcp_f32_e32 v99, v99
	v_rcp_f32_e32 v103, v103

;   DI void operator()(g8::Acc& acc, int pm, int pn, int wr, int wc, int fr, int fq) const {
;     ...
;           if (seg < 2) {
;             if (bj == 0) {
;               const f32x4 c0 = gld<f32x4>(rope, (unsigned)row * 64u), c1 = gld<f32x4>(rope, (unsigned)row * 64u + 16u), s0 = gld<f32x4>(rope, (unsigned)row * 64u + 32u) * sgn, s1 = gld<f32x4>(rope, (unsigned)row * 64u + 48u) * sgn;
;               f32x4 p0, p1;
; #pragma unroll
;               for (int e = 0; e < 4; ++e) { p0[e] = __shfl_xor(o0[e], 16); p1[e] = __shfl_xor(o1[e], 16); }
;               const f32x4 r0 = o0 * c0 + p0 * s0, r1 = o1 * c1 + p1 * s1;
; #pragma unroll
;               for (int e = 0; e < 4; ++e) { o0[e] = use ? r0[e] : o0[e]; o1[e] = use ? r1[e] : o1[e]; }
;             }
;             o0 = o0 * qs; o1 = o1 * qs;
.LBB0_209:
	v_and_b32_e32 v113, 64, v165
	v_xor_b32_e32 v112, 16, v165
	v_add_u32_e32 v113, 64, v113
	v_cmp_lt_i32_e32 vcc, v112, v113
	s_waitcnt vmcnt(2)
	v_pk_mul_f32 v[102:103], v[138:139], v[238:239]
	v_cndmask_b32_e32 v112, v165, v112, vcc
	v_lshlrev_b32_e32 v119, 2, v112
	ds_bpermute_b32 v112, v119, v92
	ds_bpermute_b32 v114, v119, v88
	ds_bpermute_b32 v113, v119, v93
	ds_bpermute_b32 v115, v119, v89
	ds_bpermute_b32 v116, v119, v94
	ds_bpermute_b32 v118, v119, v90
	ds_bpermute_b32 v117, v119, v95
	ds_bpermute_b32 v119, v119, v91
	v_pk_mul_f32 v[110:111], v[138:139], v[246:247]
	v_pk_mul_f32 v[108:109], v[136:137], v[244:245]
	v_pk_mul_f32 v[100:101], v[136:137], v[236:237]
	s_waitcnt lgkmcnt(5)
	v_pk_mul_f32 v[108:109], v[108:109], v[112:113]
	s_waitcnt lgkmcnt(1)
	v_pk_mul_f32 v[110:111], v[110:111], v[116:117]
	v_pk_mul_f32 v[100:101], v[100:101], v[114:115]
	s_waitcnt lgkmcnt(0)
	v_pk_mul_f32 v[102:103], v[102:103], v[118:119]
	v_pk_fma_f32 v[106:107], v[94:95], v[242:243], v[110:111]
	v_pk_fma_f32 v[104:105], v[92:93], v[240:241], v[108:109]
	v_pk_fma_f32 v[98:99], v[90:91], v[234:235], v[102:103]
	v_pk_fma_f32 v[96:97], v[88:89], v[232:233], v[100:101]
	v_cndmask_b32_e64 v93, v93, v105, s[4:5]
	v_cndmask_b32_e64 v92, v92, v104, s[4:5]
	v_cndmask_b32_e64 v95, v95, v107, s[4:5]
	v_cndmask_b32_e64 v94, v94, v106, s[4:5]
	v_cndmask_b32_e64 v89, v89, v97, s[4:5]
	v_cndmask_b32_e64 v88, v88, v96, s[4:5]
	v_cndmask_b32_e64 v91, v91, v99, s[4:5]
	v_cndmask_b32_e64 v90, v90, v98, s[4:5]
	v_mov_b32_e32 v100, v144
	v_mov_b32_e32 v101, v144
	v_pk_mul_f32 v[98:99], v[100:101], v[94:95]
	v_pk_mul_f32 v[96:97], v[144:145], v[92:93]
	v_pk_mul_f32 v[102:103], v[100:101], v[90:91]
	v_pk_mul_f32 v[100:101], v[144:145], v[88:89]

;   DI void operator()(g8::Acc& acc, int pm, int pn, int wr, int wc, int fr, int fq) const {
;     ...
;     if (seg < 5) { dst = slot(p, seg + 1); ld = 1024; cofs = seg * 1024; } else { dst = (bf16_t*)p.out; ld = 2048; cofs = 5 * 1024; }
;     const float qs = (seg == 0) ? 0.125f * LOG2E : 1.0f;
;     const float sgn = (fq == 0) ? -1.0f : 1.0f; const bool use = fq < 2;
;     const unsigned col0 = (unsigned)(pn * BM + wc * 64 - cofs);
; #pragma unroll
;     for (int ai = 0; ai < 2; ++ai)
; #pragma unroll
;       for (int m = 0; m < 4; ++m) {
;         const int row0 = pm * BM + ai * HALF + wr * 64 + m * 16, row = row0 + fr;
;         u32x4 w[2];
; #pragma unroll
;         for (int bj = 0; bj < 2; ++bj) {
;           f32x4 o0 = acc[ai][bj][m][0], o1 = acc[ai][bj][m][1];
;           if (seg < 2) {
;             if (bj == 0) {
;               const f32x4 c0 = gld<f32x4>(rope, (unsigned)row * 64u), c1 = gld<f32x4>(rope, (unsigned)row * 64u + 16u), s0 = gld<f32x4>(rope, (unsigned)row * 64u + 32u) * sgn, s1 = gld<f32x4>(rope, (unsigned)row * 64u + 48u) * sgn;
;               f32x4 p0, p1;
; #pragma unroll
;               for (int e = 0; e < 4; ++e) { p0[e] = __shfl_xor(o0[e], 16); p1[e] = __shfl_xor(o1[e], 16); }
;               const f32x4 r0 = o0 * c0 + p0 * s0, r1 = o1 * c1 + p1 * s1;
; #pragma unroll
;               for (int e = 0; e < 4; ++e) { o0[e] = use ? r0[e] : o0[e]; o1[e] = use ? r1[e] : o1[e]; }
;             }
;             o0 = o0 * qs; o1 = o1 * qs;
;           } else if (seg == 3 || seg == 4) {
; #pragma unroll
;             for (int e = 0; e < 4; ++e) {
;               { const float xx = o0[e], y2 = (-2.0f * 0.7978845608028654f * LOG2E) * (xx + 0.044715f * xx * xx * xx); o0[e] = xx * __builtin_amdgcn_rcpf(1.0f + __builtin_amdgcn_exp2f(y2)); }
;               { const float xx = o1[e], y2 = (-2.0f * 0.7978845608028654f * LOG2E) * (xx + 0.044715f * xx * xx * xx); o1[e] = xx * __builtin_amdgcn_rcpf(1.0f + __builtin_amdgcn_exp2f(y2)); }
;             }
;           } else if (seg >= 5) {
; #pragma unroll
;             for (int e = 0; e < 4; ++e) { o0[e] = __builtin_amdgcn_rcpf(1.0f + __builtin_amdgcn_exp2f(-LOG2E * o0[e])); o1[e] = __builtin_amdgcn_rcpf(1.0f + __builtin_amdgcn_exp2f(-LOG2E * o1[e])); }
;           }
;           w[bj] = pk8(o0, o1);
;         }
;         st_rows16<true>(dst, ld * 2u, (unsigned)row0, col0, fr, fq, w[0], w[1]);
.LBB0_220:
	v_cvt_pk_bf16_f32 v80, v88, v89
	v_mov_b32_e32 v88, 0
	v_cvt_pk_bf16_f32 v81, v96, v97
	v_cvt_pk_bf16_f32 v84, v90, v91
	v_cvt_pk_bf16_f32 v85, v92, v93
	v_cvt_pk_bf16_f32 v86, v94, v95
	v_mov_b32_dpp v88, v80 row_ror:8 row_mask:0xf bank_mask:0xf
	v_mov_b32_e32 v89, 0
	v_mov_b32_e32 v90, 0
	v_mov_b32_e32 v91, 0
	v_cvt_pk_bf16_f32 v82, v98, v99
	v_cvt_pk_bf16_f32 v83, v100, v101
	v_cvt_pk_bf16_f32 v87, v102, v103
	v_mov_b32_dpp v89, v84 row_ror:8 row_mask:0xf bank_mask:0xf
	v_mov_b32_dpp v90, v85 row_ror:8 row_mask:0xf bank_mask:0xf
	v_mov_b32_dpp v91, v86 row_ror:8 row_mask:0xf bank_mask:0xf
	v_cndmask_b32_e64 v80, v81, v88, s[6:7]
	v_cndmask_b32_e64 v84, v88, v81, s[6:7]
	v_or_b32_e32 v88, s20, v158
	v_cndmask_b32_e64 v81, v82, v89, s[6:7]
	v_cndmask_b32_e64 v85, v89, v82, s[6:7]
	v_cndmask_b32_e64 v82, v83, v90, s[6:7]
	v_cndmask_b32_e64 v86, v90, v83, s[6:7]
	v_cndmask_b32_e64 v83, v87, v91, s[6:7]
	v_lshl_add_u32 v89, v88, s19, v147
	s_and_b64 vcc, exec, s[10:11]
	s_cbranch_vccz .Lrope_pf_skip3
	v_add_u32_e32 v248, 0xc00, v249
	global_load_dwordx4 v[232:235], v248, s[74:75] offset:16
	global_load_dwordx4 v[236:239], v248, s[74:75] offset:48
	global_load_dwordx4 v[240:243], v248, s[74:75]
	global_load_dwordx4 v[244:247], v248, s[74:75] offset:32
.Lrope_pf_skip3:
	global_store_dwordx4 v89, v[80:83], s[90:91] nt
	v_cndmask_b32_e64 v87, v91, v87, s[6:7]
	s_and_b64 vcc, exec, s[10:11]
	v_or_b32_e32 v80, 8, v88
	v_lshl_add_u32 v80, v80, s19, v146
	s_mov_b64 s[0:1], -1
	global_store_dwordx4 v80, v[84:87], s[90:91] nt
	s_cbranch_vccnz .LBB0_228
	s_and_b64 vcc, exec, s[8:9]
	s_cbranch_vccnz .LBB0_225
	s_andn2_b64 vcc, exec, s[88:89]
	v_mov_b32_e32 v83, v79
	v_mov_b32_e32 v82, v78
	v_mov_b32_e32 v81, v77
	v_mov_b32_e32 v80, v76
	v_mov_b32_e32 v87, v75
	v_mov_b32_e32 v86, v74
	v_mov_b32_e32 v85, v73
	v_mov_b32_e32 v84, v72
	s_cbranch_vccnz .LBB0_224
	v_mul_f32_e32 v81, 0xbfb8aa3b, v72
	v_exp_f32_e32 v81, v81
	v_mul_f32_e32 v82, 0xbfb8aa3b, v77
	v_mul_f32_e32 v83, 0xbfb8aa3b, v73
	v_exp_f32_e32 v82, v82
	v_exp_f32_e32 v83, v83
	v_add_f32_e32 v81, 1.0, v81
	v_rcp_f32_e32 v84, v81
	v_add_f32_e32 v81, 1.0, v82
	v_add_f32_e32 v82, 1.0, v83
	v_mul_f32_e32 v83, 0xbfb8aa3b, v78
	v_mul_f32_e32 v85, 0xbfb8aa3b, v74
	v_exp_f32_e32 v83, v83
	v_exp_f32_e32 v86, v85
	v_rcp_f32_e32 v85, v82
	v_mul_f32_e32 v80, 0xbfb8aa3b, v76
	v_add_f32_e32 v82, 1.0, v83
	v_add_f32_e32 v83, 1.0, v86
	v_mul_f32_e32 v86, 0xbfb8aa3b, v79
	v_exp_f32_e32 v87, v86
	v_mul_f32_e32 v86, 0xbfb8aa3b, v75
	v_exp_f32_e32 v80, v80
	v_exp_f32_e32 v88, v86
	v_rcp_f32_e32 v86, v83
	v_add_f32_e32 v83, 1.0, v87
	v_add_f32_e32 v80, 1.0, v80
	v_add_f32_e32 v87, 1.0, v88
	v_rcp_f32_e32 v80, v80
	v_rcp_f32_e32 v81, v81
	v_rcp_f32_e32 v82, v82
	v_rcp_f32_e32 v83, v83
	v_rcp_f32_e32 v87, v87

;   DI void operator()(g8::Acc& acc, int pm, int pn, int wr, int wc, int fr, int fq) const {
;     ...
;           if (seg < 2) {
;             if (bj == 0) {
;               const f32x4 c0 = gld<f32x4>(rope, (unsigned)row * 64u), c1 = gld<f32x4>(rope, (unsigned)row * 64u + 16u), s0 = gld<f32x4>(rope, (unsigned)row * 64u + 32u) * sgn, s1 = gld<f32x4>(rope, (unsigned)row * 64u + 48u) * sgn;
;               f32x4 p0, p1;
; #pragma unroll
;               for (int e = 0; e < 4; ++e) { p0[e] = __shfl_xor(o0[e], 16); p1[e] = __shfl_xor(o1[e], 16); }
;               const f32x4 r0 = o0 * c0 + p0 * s0, r1 = o1 * c1 + p1 * s1;
; #pragma unroll
;               for (int e = 0; e < 4; ++e) { o0[e] = use ? r0[e] : o0[e]; o1[e] = use ? r1[e] : o1[e]; }
;             }
;             o0 = o0 * qs; o1 = o1 * qs;
.LBB0_229:
	v_and_b32_e32 v97, 64, v165
	v_xor_b32_e32 v96, 16, v165
	v_add_u32_e32 v97, 64, v97
	v_cmp_lt_i32_e32 vcc, v96, v97
	s_waitcnt vmcnt(2)
	v_pk_mul_f32 v[86:87], v[138:139], v[238:239]
	v_cndmask_b32_e32 v96, v165, v96, vcc
	v_lshlrev_b32_e32 v103, 2, v96
	ds_bpermute_b32 v96, v103, v76
	ds_bpermute_b32 v98, v103, v72
	ds_bpermute_b32 v97, v103, v77
	ds_bpermute_b32 v99, v103, v73
	ds_bpermute_b32 v100, v103, v78
	ds_bpermute_b32 v102, v103, v74
	ds_bpermute_b32 v101, v103, v79
	ds_bpermute_b32 v103, v103, v75
	v_pk_mul_f32 v[94:95], v[138:139], v[246:247]
	v_pk_mul_f32 v[92:93], v[136:137], v[244:245]
	v_pk_mul_f32 v[84:85], v[136:137], v[236:237]
	s_waitcnt lgkmcnt(5)
	v_pk_mul_f32 v[92:93], v[92:93], v[96:97]
	s_waitcnt lgkmcnt(1)
	v_pk_mul_f32 v[94:95], v[94:95], v[100:101]
	v_pk_mul_f32 v[84:85], v[84:85], v[98:99]
	s_waitcnt lgkmcnt(0)
	v_pk_mul_f32 v[86:87], v[86:87], v[102:103]
	v_pk_fma_f32 v[90:91], v[78:79], v[242:243], v[94:95]
	v_pk_fma_f32 v[88:89], v[76:77], v[240:241], v[92:93]
	v_pk_fma_f32 v[82:83], v[74:75], v[234:235], v[86:87]
	v_pk_fma_f32 v[80:81], v[72:73], v[232:233], v[84:85]
	v_cndmask_b32_e64 v77, v77, v89, s[4:5]
	v_cndmask_b32_e64 v76, v76, v88, s[4:5]
	v_cndmask_b32_e64 v79, v79, v91, s[4:5]
	v_cndmask_b32_e64 v78, v78, v90, s[4:5]
	v_cndmask_b32_e64 v73, v73, v81, s[4:5]
	v_cndmask_b32_e64 v72, v72, v80, s[4:5]
	v_cndmask_b32_e64 v75, v75, v83, s[4:5]
	v_cndmask_b32_e64 v74, v74, v82, s[4:5]
	v_mov_b32_e32 v84, v144
	v_mov_b32_e32 v85, v144
	v_pk_mul_f32 v[82:83], v[84:85], v[78:79]
	v_pk_mul_f32 v[80:81], v[144:145], v[76:77]
	v_pk_mul_f32 v[86:87], v[84:85], v[74:75]
	v_pk_mul_f32 v[84:85], v[144:145], v[72:73]

;   DI void operator()(g8::Acc& acc, int pm, int pn, int wr, int wc, int fr, int fq) const {
;     ...
;     if (seg < 5) { dst = slot(p, seg + 1); ld = 1024; cofs = seg * 1024; } else { dst = (bf16_t*)p.out; ld = 2048; cofs = 5 * 1024; }
;     const float qs = (seg == 0) ? 0.125f * LOG2E : 1.0f;
;     const float sgn = (fq == 0) ? -1.0f : 1.0f; const bool use = fq < 2;
;     const unsigned col0 = (unsigned)(pn * BM + wc * 64 - cofs);
; #pragma unroll
;     for (int ai = 0; ai < 2; ++ai)
; #pragma unroll
;       for (int m = 0; m < 4; ++m) {
;         const int row0 = pm * BM + ai * HALF + wr * 64 + m * 16, row = row0 + fr;
;         u32x4 w[2];
; #pragma unroll
;         for (int bj = 0; bj < 2; ++bj) {
;           f32x4 o0 = acc[ai][bj][m][0], o1 = acc[ai][bj][m][1];
;           if (seg < 2) {
;             if (bj == 0) {
;               const f32x4 c0 = gld<f32x4>(rope, (unsigned)row * 64u), c1 = gld<f32x4>(rope, (unsigned)row * 64u + 16u), s0 = gld<f32x4>(rope, (unsigned)row * 64u + 32u) * sgn, s1 = gld<f32x4>(rope, (unsigned)row * 64u + 48u) * sgn;
;               f32x4 p0, p1;
; #pragma unroll
;               for (int e = 0; e < 4; ++e) { p0[e] = __shfl_xor(o0[e], 16); p1[e] = __shfl_xor(o1[e], 16); }
;               const f32x4 r0 = o0 * c0 + p0 * s0, r1 = o1 * c1 + p1 * s1;
; #pragma unroll
;               for (int e = 0; e < 4; ++e) { o0[e] = use ? r0[e] : o0[e]; o1[e] = use ? r1[e] : o1[e]; }
;             }
;             o0 = o0 * qs; o1 = o1 * qs;
;           } else if (seg == 3 || seg == 4) {
; #pragma unroll
;             for (int e = 0; e < 4; ++e) {
;               { const float xx = o0[e], y2 = (-2.0f * 0.7978845608028654f * LOG2E) * (xx + 0.044715f * xx * xx * xx); o0[e] = xx * __builtin_amdgcn_rcpf(1.0f + __builtin_amdgcn_exp2f(y2)); }
;               { const float xx = o1[e], y2 = (-2.0f * 0.7978845608028654f * LOG2E) * (xx + 0.044715f * xx * xx * xx); o1[e] = xx * __builtin_amdgcn_rcpf(1.0f + __builtin_amdgcn_exp2f(y2)); }
;             }
;           } else if (seg >= 5) {
; #pragma unroll
;             for (int e = 0; e < 4; ++e) { o0[e] = __builtin_amdgcn_rcpf(1.0f + __builtin_amdgcn_exp2f(-LOG2E * o0[e])); o1[e] = __builtin_amdgcn_rcpf(1.0f + __builtin_amdgcn_exp2f(-LOG2E * o1[e])); }
;           }
;           w[bj] = pk8(o0, o1);
;         }
;         st_rows16<true>(dst, ld * 2u, (unsigned)row0, col0, fr, fq, w[0], w[1]);
.LBB0_240:
	v_cvt_pk_bf16_f32 v64, v72, v73
	v_mov_b32_e32 v72, 0
	v_cvt_pk_bf16_f32 v65, v80, v81
	v_cvt_pk_bf16_f32 v68, v74, v75
	v_cvt_pk_bf16_f32 v69, v76, v77
	v_cvt_pk_bf16_f32 v70, v78, v79
	v_mov_b32_dpp v72, v64 row_ror:8 row_mask:0xf bank_mask:0xf
	v_mov_b32_e32 v73, 0
	v_mov_b32_e32 v74, 0
	v_mov_b32_e32 v75, 0
	v_cvt_pk_bf16_f32 v66, v82, v83
	v_cvt_pk_bf16_f32 v67, v84, v85
	v_cvt_pk_bf16_f32 v71, v86, v87
	v_mov_b32_dpp v73, v68 row_ror:8 row_mask:0xf bank_mask:0xf
	v_mov_b32_dpp v74, v69 row_ror:8 row_mask:0xf bank_mask:0xf
	v_mov_b32_dpp v75, v70 row_ror:8 row_mask:0xf bank_mask:0xf
	v_cndmask_b32_e64 v64, v65, v72, s[6:7]
	v_cndmask_b32_e64 v68, v72, v65, s[6:7]
	v_or_b32_e32 v72, s20, v158
	v_cndmask_b32_e64 v65, v66, v73, s[6:7]
	v_cndmask_b32_e64 v69, v73, v66, s[6:7]
	v_cndmask_b32_e64 v66, v67, v74, s[6:7]
	v_cndmask_b32_e64 v70, v74, v67, s[6:7]
	v_cndmask_b32_e64 v67, v71, v75, s[6:7]
	v_lshl_add_u32 v73, v72, s19, v147
	s_and_b64 vcc, exec, s[10:11]
	s_cbranch_vccz .Lrope_pf_skip4
	v_add_u32_e32 v248, 0x2000, v249
	global_load_dwordx4 v[232:235], v248, s[74:75] offset:16
	global_load_dwordx4 v[236:239], v248, s[74:75] offset:48
	global_load_dwordx4 v[240:243], v248, s[74:75]
	global_load_dwordx4 v[244:247], v248, s[74:75] offset:32
.Lrope_pf_skip4:
	global_store_dwordx4 v73, v[64:67], s[90:91] nt
	v_cndmask_b32_e64 v71, v75, v71, s[6:7]
	s_and_b64 vcc, exec, s[10:11]
	v_or_b32_e32 v64, 8, v72
	v_lshl_add_u32 v64, v64, s19, v146
	s_mov_b64 s[0:1], -1
	global_store_dwordx4 v64, v[68:71], s[90:91] nt
	s_cbranch_vccnz .LBB0_248
	s_and_b64 vcc, exec, s[8:9]
	s_cbranch_vccnz .LBB0_245
	s_andn2_b64 vcc, exec, s[88:89]
	v_mov_b32_e32 v67, v63
	v_mov_b32_e32 v66, v62
	v_mov_b32_e32 v65, v61
	v_mov_b32_e32 v64, v60
	v_mov_b32_e32 v71, v59
	v_mov_b32_e32 v70, v58
	v_mov_b32_e32 v69, v57
	v_mov_b32_e32 v68, v56
	s_cbranch_vccnz .LBB0_244
	v_mul_f32_e32 v65, 0xbfb8aa3b, v56
	v_exp_f32_e32 v65, v65
	v_mul_f32_e32 v66, 0xbfb8aa3b, v61
	v_mul_f32_e32 v67, 0xbfb8aa3b, v57
	v_exp_f32_e32 v66, v66
	v_exp_f32_e32 v67, v67
	v_add_f32_e32 v65, 1.0, v65
	v_rcp_f32_e32 v68, v65
	v_add_f32_e32 v65, 1.0, v66
	v_add_f32_e32 v66, 1.0, v67
	v_mul_f32_e32 v67, 0xbfb8aa3b, v62
	v_mul_f32_e32 v69, 0xbfb8aa3b, v58
	v_exp_f32_e32 v67, v67
	v_exp_f32_e32 v70, v69
	v_rcp_f32_e32 v69, v66
	v_mul_f32_e32 v64, 0xbfb8aa3b, v60
	v_add_f32_e32 v66, 1.0, v67
	v_add_f32_e32 v67, 1.0, v70
	v_mul_f32_e32 v70, 0xbfb8aa3b, v63
	v_exp_f32_e32 v71, v70
	v_mul_f32_e32 v70, 0xbfb8aa3b, v59
	v_exp_f32_e32 v64, v64
	v_exp_f32_e32 v72, v70
	v_rcp_f32_e32 v70, v67
	v_add_f32_e32 v67, 1.0, v71
	v_add_f32_e32 v64, 1.0, v64
	v_add_f32_e32 v71, 1.0, v72
	v_rcp_f32_e32 v64, v64
	v_rcp_f32_e32 v65, v65
	v_rcp_f32_e32 v66, v66
	v_rcp_f32_e32 v67, v67
	v_rcp_f32_e32 v71, v71

;   DI void operator()(g8::Acc& acc, int pm, int pn, int wr, int wc, int fr, int fq) const {
;     ...
;           if (seg < 2) {
;             if (bj == 0) {
;               const f32x4 c0 = gld<f32x4>(rope, (unsigned)row * 64u), c1 = gld<f32x4>(rope, (unsigned)row * 64u + 16u), s0 = gld<f32x4>(rope, (unsigned)row * 64u + 32u) * sgn, s1 = gld<f32x4>(rope, (unsigned)row * 64u + 48u) * sgn;
;               f32x4 p0, p1;
; #pragma unroll
;               for (int e = 0; e < 4; ++e) { p0[e] = __shfl_xor(o0[e], 16); p1[e] = __shfl_xor(o1[e], 16); }
;               const f32x4 r0 = o0 * c0 + p0 * s0, r1 = o1 * c1 + p1 * s1;
; #pragma unroll
;               for (int e = 0; e < 4; ++e) { o0[e] = use ? r0[e] : o0[e]; o1[e] = use ? r1[e] : o1[e]; }
;             }
;             o0 = o0 * qs; o1 = o1 * qs;
.LBB0_249:
	v_and_b32_e32 v81, 64, v165
	v_xor_b32_e32 v80, 16, v165
	v_add_u32_e32 v81, 64, v81
	v_cmp_lt_i32_e32 vcc, v80, v81
	s_waitcnt vmcnt(2)
	v_pk_mul_f32 v[70:71], v[138:139], v[238:239]
	v_cndmask_b32_e32 v80, v165, v80, vcc
	v_lshlrev_b32_e32 v87, 2, v80
	ds_bpermute_b32 v80, v87, v60
	ds_bpermute_b32 v82, v87, v56
	ds_bpermute_b32 v81, v87, v61
	ds_bpermute_b32 v83, v87, v57
	ds_bpermute_b32 v84, v87, v62
	ds_bpermute_b32 v86, v87, v58
	ds_bpermute_b32 v85, v87, v63
	ds_bpermute_b32 v87, v87, v59
	v_pk_mul_f32 v[78:79], v[138:139], v[246:247]
	v_pk_mul_f32 v[76:77], v[136:137], v[244:245]
	v_pk_mul_f32 v[68:69], v[136:137], v[236:237]
	s_waitcnt lgkmcnt(5)
	v_pk_mul_f32 v[76:77], v[76:77], v[80:81]
	s_waitcnt lgkmcnt(1)
	v_pk_mul_f32 v[78:79], v[78:79], v[84:85]
	v_pk_mul_f32 v[68:69], v[68:69], v[82:83]
	s_waitcnt lgkmcnt(0)
	v_pk_mul_f32 v[70:71], v[70:71], v[86:87]
	v_pk_fma_f32 v[74:75], v[62:63], v[242:243], v[78:79]
	v_pk_fma_f32 v[72:73], v[60:61], v[240:241], v[76:77]
	v_pk_fma_f32 v[66:67], v[58:59], v[234:235], v[70:71]
	v_pk_fma_f32 v[64:65], v[56:57], v[232:233], v[68:69]
	v_cndmask_b32_e64 v61, v61, v73, s[4:5]
	v_cndmask_b32_e64 v60, v60, v72, s[4:5]
	v_cndmask_b32_e64 v63, v63, v75, s[4:5]
	v_cndmask_b32_e64 v62, v62, v74, s[4:5]
	v_cndmask_b32_e64 v57, v57, v65, s[4:5]
	v_cndmask_b32_e64 v56, v56, v64, s[4:5]
	v_cndmask_b32_e64 v59, v59, v67, s[4:5]
	v_cndmask_b32_e64 v58, v58, v66, s[4:5]
	v_mov_b32_e32 v68, v144
	v_mov_b32_e32 v69, v144
	v_pk_mul_f32 v[66:67], v[68:69], v[62:63]
	v_pk_mul_f32 v[64:65], v[144:145], v[60:61]
	v_pk_mul_f32 v[70:71], v[68:69], v[58:59]
	v_pk_mul_f32 v[68:69], v[144:145], v[56:57]

;   DI void operator()(g8::Acc& acc, int pm, int pn, int wr, int wc, int fr, int fq) const {
;     ...
;     if (seg < 5) { dst = slot(p, seg + 1); ld = 1024; cofs = seg * 1024; } else { dst = (bf16_t*)p.out; ld = 2048; cofs = 5 * 1024; }
;     const float qs = (seg == 0) ? 0.125f * LOG2E : 1.0f;
;     const float sgn = (fq == 0) ? -1.0f : 1.0f; const bool use = fq < 2;
;     const unsigned col0 = (unsigned)(pn * BM + wc * 64 - cofs);
; #pragma unroll
;     for (int ai = 0; ai < 2; ++ai)
; #pragma unroll
;       for (int m = 0; m < 4; ++m) {
;         const int row0 = pm * BM + ai * HALF + wr * 64 + m * 16, row = row0 + fr;
;         u32x4 w[2];
; #pragma unroll
;         for (int bj = 0; bj < 2; ++bj) {
;           f32x4 o0 = acc[ai][bj][m][0], o1 = acc[ai][bj][m][1];
;           if (seg < 2) {
;             if (bj == 0) {
;               const f32x4 c0 = gld<f32x4>(rope, (unsigned)row * 64u), c1 = gld<f32x4>(rope, (unsigned)row * 64u + 16u), s0 = gld<f32x4>(rope, (unsigned)row * 64u + 32u) * sgn, s1 = gld<f32x4>(rope, (unsigned)row * 64u + 48u) * sgn;
;               f32x4 p0, p1;
; #pragma unroll
;               for (int e = 0; e < 4; ++e) { p0[e] = __shfl_xor(o0[e], 16); p1[e] = __shfl_xor(o1[e], 16); }
;               const f32x4 r0 = o0 * c0 + p0 * s0, r1 = o1 * c1 + p1 * s1;
; #pragma unroll
;               for (int e = 0; e < 4; ++e) { o0[e] = use ? r0[e] : o0[e]; o1[e] = use ? r1[e] : o1[e]; }
;             }
;             o0 = o0 * qs; o1 = o1 * qs;
;           } else if (seg == 3 || seg == 4) {
; #pragma unroll
;             for (int e = 0; e < 4; ++e) {
;               { const float xx = o0[e], y2 = (-2.0f * 0.7978845608028654f * LOG2E) * (xx + 0.044715f * xx * xx * xx); o0[e] = xx * __builtin_amdgcn_rcpf(1.0f + __builtin_amdgcn_exp2f(y2)); }
;               { const float xx = o1[e], y2 = (-2.0f * 0.7978845608028654f * LOG2E) * (xx + 0.044715f * xx * xx * xx); o1[e] = xx * __builtin_amdgcn_rcpf(1.0f + __builtin_amdgcn_exp2f(y2)); }
;             }
;           } else if (seg >= 5) {
; #pragma unroll
;             for (int e = 0; e < 4; ++e) { o0[e] = __builtin_amdgcn_rcpf(1.0f + __builtin_amdgcn_exp2f(-LOG2E * o0[e])); o1[e] = __builtin_amdgcn_rcpf(1.0f + __builtin_amdgcn_exp2f(-LOG2E * o1[e])); }
;           }
;           w[bj] = pk8(o0, o1);
;         }
;         st_rows16<true>(dst, ld * 2u, (unsigned)row0, col0, fr, fq, w[0], w[1]);
.LBB0_260:
	v_cvt_pk_bf16_f32 v48, v56, v57
	v_mov_b32_e32 v56, 0
	v_cvt_pk_bf16_f32 v49, v64, v65
	v_cvt_pk_bf16_f32 v52, v58, v59
	v_cvt_pk_bf16_f32 v53, v60, v61
	v_cvt_pk_bf16_f32 v54, v62, v63
	v_mov_b32_dpp v56, v48 row_ror:8 row_mask:0xf bank_mask:0xf
	v_mov_b32_e32 v57, 0
	v_mov_b32_e32 v58, 0
	v_mov_b32_e32 v59, 0
	v_cvt_pk_bf16_f32 v50, v66, v67
	v_cvt_pk_bf16_f32 v51, v68, v69
	v_cvt_pk_bf16_f32 v55, v70, v71
	v_mov_b32_dpp v57, v52 row_ror:8 row_mask:0xf bank_mask:0xf
	v_mov_b32_dpp v58, v53 row_ror:8 row_mask:0xf bank_mask:0xf
	v_mov_b32_dpp v59, v54 row_ror:8 row_mask:0xf bank_mask:0xf
	v_cndmask_b32_e64 v48, v49, v56, s[6:7]
	v_cndmask_b32_e64 v52, v56, v49, s[6:7]
	v_or_b32_e32 v56, s20, v158
	v_cndmask_b32_e64 v49, v50, v57, s[6:7]
	v_cndmask_b32_e64 v53, v57, v50, s[6:7]
	v_cndmask_b32_e64 v50, v51, v58, s[6:7]
	v_cndmask_b32_e64 v54, v58, v51, s[6:7]
	v_cndmask_b32_e64 v51, v55, v59, s[6:7]
	v_lshl_add_u32 v57, v56, s19, v147
	s_and_b64 vcc, exec, s[10:11]
	s_cbranch_vccz .Lrope_pf_skip5
	v_add_u32_e32 v248, 0x2400, v249
	global_load_dwordx4 v[232:235], v248, s[74:75] offset:16
	global_load_dwordx4 v[236:239], v248, s[74:75] offset:48
	global_load_dwordx4 v[240:243], v248, s[74:75]
	global_load_dwordx4 v[244:247], v248, s[74:75] offset:32
.Lrope_pf_skip5:
	global_store_dwordx4 v57, v[48:51], s[90:91] nt
	v_cndmask_b32_e64 v55, v59, v55, s[6:7]
	s_and_b64 vcc, exec, s[10:11]
	v_or_b32_e32 v48, 8, v56
	v_lshl_add_u32 v48, v48, s19, v146
	s_mov_b64 s[0:1], -1
	global_store_dwordx4 v48, v[52:55], s[90:91] nt
	s_cbranch_vccnz .LBB0_268
	s_and_b64 vcc, exec, s[8:9]
	s_cbranch_vccnz .LBB0_265
	s_andn2_b64 vcc, exec, s[88:89]
	v_mov_b32_e32 v51, v47
	v_mov_b32_e32 v50, v46
	v_mov_b32_e32 v49, v45
	v_mov_b32_e32 v48, v44
	v_mov_b32_e32 v55, v43
	v_mov_b32_e32 v54, v42
	v_mov_b32_e32 v53, v41
	v_mov_b32_e32 v52, v40
	s_cbranch_vccnz .LBB0_264
	v_mul_f32_e32 v49, 0xbfb8aa3b, v40
	v_exp_f32_e32 v49, v49
	v_mul_f32_e32 v50, 0xbfb8aa3b, v45
	v_mul_f32_e32 v51, 0xbfb8aa3b, v41
	v_exp_f32_e32 v50, v50
	v_exp_f32_e32 v51, v51
	v_add_f32_e32 v49, 1.0, v49
	v_rcp_f32_e32 v52, v49
	v_add_f32_e32 v49, 1.0, v50
	v_add_f32_e32 v50, 1.0, v51
	v_mul_f32_e32 v51, 0xbfb8aa3b, v46
	v_mul_f32_e32 v53, 0xbfb8aa3b, v42
	v_exp_f32_e32 v51, v51
	v_exp_f32_e32 v54, v53
	v_rcp_f32_e32 v53, v50
	v_mul_f32_e32 v48, 0xbfb8aa3b, v44
	v_add_f32_e32 v50, 1.0, v51
	v_add_f32_e32 v51, 1.0, v54
	v_mul_f32_e32 v54, 0xbfb8aa3b, v47
	v_exp_f32_e32 v55, v54
	v_mul_f32_e32 v54, 0xbfb8aa3b, v43
	v_exp_f32_e32 v48, v48
	v_exp_f32_e32 v56, v54
	v_rcp_f32_e32 v54, v51
	v_add_f32_e32 v51, 1.0, v55
	v_add_f32_e32 v48, 1.0, v48
	v_add_f32_e32 v55, 1.0, v56
	v_rcp_f32_e32 v48, v48
	v_rcp_f32_e32 v49, v49
	v_rcp_f32_e32 v50, v50
	v_rcp_f32_e32 v51, v51
	v_rcp_f32_e32 v55, v55

;   DI void operator()(g8::Acc& acc, int pm, int pn, int wr, int wc, int fr, int fq) const {
;     ...
;           if (seg < 2) {
;             if (bj == 0) {
;               const f32x4 c0 = gld<f32x4>(rope, (unsigned)row * 64u), c1 = gld<f32x4>(rope, (unsigned)row * 64u + 16u), s0 = gld<f32x4>(rope, (unsigned)row * 64u + 32u) * sgn, s1 = gld<f32x4>(rope, (unsigned)row * 64u + 48u) * sgn;
;               f32x4 p0, p1;
; #pragma unroll
;               for (int e = 0; e < 4; ++e) { p0[e] = __shfl_xor(o0[e], 16); p1[e] = __shfl_xor(o1[e], 16); }
;               const f32x4 r0 = o0 * c0 + p0 * s0, r1 = o1 * c1 + p1 * s1;
; #pragma unroll
;               for (int e = 0; e < 4; ++e) { o0[e] = use ? r0[e] : o0[e]; o1[e] = use ? r1[e] : o1[e]; }
;             }
;             o0 = o0 * qs; o1 = o1 * qs;
.LBB0_269:
	v_and_b32_e32 v65, 64, v165
	v_xor_b32_e32 v64, 16, v165
	v_add_u32_e32 v65, 64, v65
	v_cmp_lt_i32_e32 vcc, v64, v65
	s_waitcnt vmcnt(2)
	v_pk_mul_f32 v[54:55], v[138:139], v[238:239]
	v_cndmask_b32_e32 v64, v165, v64, vcc
	v_lshlrev_b32_e32 v71, 2, v64
	ds_bpermute_b32 v64, v71, v44
	ds_bpermute_b32 v66, v71, v40
	ds_bpermute_b32 v65, v71, v45
	ds_bpermute_b32 v67, v71, v41
	ds_bpermute_b32 v68, v71, v46
	ds_bpermute_b32 v70, v71, v42
	ds_bpermute_b32 v69, v71, v47
	ds_bpermute_b32 v71, v71, v43
	v_pk_mul_f32 v[62:63], v[138:139], v[246:247]
	v_pk_mul_f32 v[60:61], v[136:137], v[244:245]
	v_pk_mul_f32 v[52:53], v[136:137], v[236:237]
	s_waitcnt lgkmcnt(5)
	v_pk_mul_f32 v[60:61], v[60:61], v[64:65]
	s_waitcnt lgkmcnt(1)
	v_pk_mul_f32 v[62:63], v[62:63], v[68:69]
	v_pk_mul_f32 v[52:53], v[52:53], v[66:67]
	s_waitcnt lgkmcnt(0)
	v_pk_mul_f32 v[54:55], v[54:55], v[70:71]
	v_pk_fma_f32 v[58:59], v[46:47], v[242:243], v[62:63]
	v_pk_fma_f32 v[56:57], v[44:45], v[240:241], v[60:61]
	v_pk_fma_f32 v[50:51], v[42:43], v[234:235], v[54:55]
	v_pk_fma_f32 v[48:49], v[40:41], v[232:233], v[52:53]
	v_cndmask_b32_e64 v45, v45, v57, s[4:5]
	v_cndmask_b32_e64 v44, v44, v56, s[4:5]
	v_cndmask_b32_e64 v47, v47, v59, s[4:5]
	v_cndmask_b32_e64 v46, v46, v58, s[4:5]
	v_cndmask_b32_e64 v41, v41, v49, s[4:5]
	v_cndmask_b32_e64 v40, v40, v48, s[4:5]
	v_cndmask_b32_e64 v43, v43, v51, s[4:5]
	v_cndmask_b32_e64 v42, v42, v50, s[4:5]
	v_mov_b32_e32 v52, v144
	v_mov_b32_e32 v53, v144
	v_pk_mul_f32 v[50:51], v[52:53], v[46:47]
	v_pk_mul_f32 v[48:49], v[144:145], v[44:45]
	v_pk_mul_f32 v[54:55], v[52:53], v[42:43]
	v_pk_mul_f32 v[52:53], v[144:145], v[40:41]

;   DI void operator()(g8::Acc& acc, int pm, int pn, int wr, int wc, int fr, int fq) const {
;     ...
;     if (seg < 5) { dst = slot(p, seg + 1); ld = 1024; cofs = seg * 1024; } else { dst = (bf16_t*)p.out; ld = 2048; cofs = 5 * 1024; }
;     const float qs = (seg == 0) ? 0.125f * LOG2E : 1.0f;
;     const float sgn = (fq == 0) ? -1.0f : 1.0f; const bool use = fq < 2;
;     const unsigned col0 = (unsigned)(pn * BM + wc * 64 - cofs);
; #pragma unroll
;     for (int ai = 0; ai < 2; ++ai)
; #pragma unroll
;       for (int m = 0; m < 4; ++m) {
;         const int row0 = pm * BM + ai * HALF + wr * 64 + m * 16, row = row0 + fr;
;         u32x4 w[2];
; #pragma unroll
;         for (int bj = 0; bj < 2; ++bj) {
;           f32x4 o0 = acc[ai][bj][m][0], o1 = acc[ai][bj][m][1];
;           if (seg < 2) {
;             if (bj == 0) {
;               const f32x4 c0 = gld<f32x4>(rope, (unsigned)row * 64u), c1 = gld<f32x4>(rope, (unsigned)row * 64u + 16u), s0 = gld<f32x4>(rope, (unsigned)row * 64u + 32u) * sgn, s1 = gld<f32x4>(rope, (unsigned)row * 64u + 48u) * sgn;
;               f32x4 p0, p1;
; #pragma unroll
;               for (int e = 0; e < 4; ++e) { p0[e] = __shfl_xor(o0[e], 16); p1[e] = __shfl_xor(o1[e], 16); }
;               const f32x4 r0 = o0 * c0 + p0 * s0, r1 = o1 * c1 + p1 * s1;
; #pragma unroll
;               for (int e = 0; e < 4; ++e) { o0[e] = use ? r0[e] : o0[e]; o1[e] = use ? r1[e] : o1[e]; }
;             }
;             o0 = o0 * qs; o1 = o1 * qs;
;           } else if (seg == 3 || seg == 4) {
; #pragma unroll
;             for (int e = 0; e < 4; ++e) {
;               { const float xx = o0[e], y2 = (-2.0f * 0.7978845608028654f * LOG2E) * (xx + 0.044715f * xx * xx * xx); o0[e] = xx * __builtin_amdgcn_rcpf(1.0f + __builtin_amdgcn_exp2f(y2)); }
;               { const float xx = o1[e], y2 = (-2.0f * 0.7978845608028654f * LOG2E) * (xx + 0.044715f * xx * xx * xx); o1[e] = xx * __builtin_amdgcn_rcpf(1.0f + __builtin_amdgcn_exp2f(y2)); }
;             }
;           } else if (seg >= 5) {
; #pragma unroll
;             for (int e = 0; e < 4; ++e) { o0[e] = __builtin_amdgcn_rcpf(1.0f + __builtin_amdgcn_exp2f(-LOG2E * o0[e])); o1[e] = __builtin_amdgcn_rcpf(1.0f + __builtin_amdgcn_exp2f(-LOG2E * o1[e])); }
;           }
;           w[bj] = pk8(o0, o1);
;         }
;         st_rows16<true>(dst, ld * 2u, (unsigned)row0, col0, fr, fq, w[0], w[1]);
.LBB0_280:
	v_cvt_pk_bf16_f32 v32, v40, v41
	v_mov_b32_e32 v40, 0
	v_cvt_pk_bf16_f32 v33, v48, v49
	v_cvt_pk_bf16_f32 v36, v42, v43
	v_cvt_pk_bf16_f32 v37, v44, v45
	v_cvt_pk_bf16_f32 v38, v46, v47
	v_mov_b32_dpp v40, v32 row_ror:8 row_mask:0xf bank_mask:0xf
	v_mov_b32_e32 v41, 0
	v_mov_b32_e32 v42, 0
	v_mov_b32_e32 v43, 0
	v_cvt_pk_bf16_f32 v34, v50, v51
	v_cvt_pk_bf16_f32 v35, v52, v53
	v_cvt_pk_bf16_f32 v39, v54, v55
	v_mov_b32_dpp v41, v36 row_ror:8 row_mask:0xf bank_mask:0xf
	v_mov_b32_dpp v42, v37 row_ror:8 row_mask:0xf bank_mask:0xf
	v_mov_b32_dpp v43, v38 row_ror:8 row_mask:0xf bank_mask:0xf
	v_cndmask_b32_e64 v32, v33, v40, s[6:7]
	v_cndmask_b32_e64 v36, v40, v33, s[6:7]
	v_or_b32_e32 v40, s20, v158
	v_cndmask_b32_e64 v33, v34, v41, s[6:7]
	v_cndmask_b32_e64 v37, v41, v34, s[6:7]
	v_cndmask_b32_e64 v34, v35, v42, s[6:7]
	v_cndmask_b32_e64 v38, v42, v35, s[6:7]
	v_cndmask_b32_e64 v35, v39, v43, s[6:7]
	v_lshl_add_u32 v41, v40, s19, v147
	s_and_b64 vcc, exec, s[10:11]
	s_cbranch_vccz .Lrope_pf_skip6
	v_add_u32_e32 v248, 0x2800, v249
	global_load_dwordx4 v[232:235], v248, s[74:75] offset:16
	global_load_dwordx4 v[236:239], v248, s[74:75] offset:48
	global_load_dwordx4 v[240:243], v248, s[74:75]
	global_load_dwordx4 v[244:247], v248, s[74:75] offset:32
.Lrope_pf_skip6:
	global_store_dwordx4 v41, v[32:35], s[90:91] nt
	v_cndmask_b32_e64 v39, v43, v39, s[6:7]
	s_and_b64 vcc, exec, s[10:11]
	v_or_b32_e32 v32, 8, v40
	v_lshl_add_u32 v32, v32, s19, v146
	s_mov_b64 s[0:1], -1
	global_store_dwordx4 v32, v[36:39], s[90:91] nt
	s_cbranch_vccnz .LBB0_288
	s_and_b64 vcc, exec, s[8:9]
	s_cbranch_vccnz .LBB0_285
	s_andn2_b64 vcc, exec, s[88:89]
	v_mov_b32_e32 v35, v31
	v_mov_b32_e32 v34, v30
	v_mov_b32_e32 v33, v29
	v_mov_b32_e32 v32, v28
	v_mov_b32_e32 v39, v27
	v_mov_b32_e32 v38, v26
	v_mov_b32_e32 v37, v25
	v_mov_b32_e32 v36, v24
	s_cbranch_vccnz .LBB0_284
	v_mul_f32_e32 v33, 0xbfb8aa3b, v24
	v_exp_f32_e32 v33, v33
	v_mul_f32_e32 v34, 0xbfb8aa3b, v29
	v_mul_f32_e32 v35, 0xbfb8aa3b, v25
	v_exp_f32_e32 v34, v34
	v_exp_f32_e32 v35, v35
	v_add_f32_e32 v33, 1.0, v33
	v_rcp_f32_e32 v36, v33
	v_add_f32_e32 v33, 1.0, v34
	v_add_f32_e32 v34, 1.0, v35
	v_mul_f32_e32 v35, 0xbfb8aa3b, v30
	v_mul_f32_e32 v37, 0xbfb8aa3b, v26
	v_exp_f32_e32 v35, v35
	v_exp_f32_e32 v38, v37
	v_rcp_f32_e32 v37, v34
	v_mul_f32_e32 v32, 0xbfb8aa3b, v28
	v_add_f32_e32 v34, 1.0, v35
	v_add_f32_e32 v35, 1.0, v38
	v_mul_f32_e32 v38, 0xbfb8aa3b, v31
	v_exp_f32_e32 v39, v38
	v_mul_f32_e32 v38, 0xbfb8aa3b, v27
	v_exp_f32_e32 v32, v32
	v_exp_f32_e32 v40, v38
	v_rcp_f32_e32 v38, v35
	v_add_f32_e32 v35, 1.0, v39
	v_add_f32_e32 v32, 1.0, v32
	v_add_f32_e32 v39, 1.0, v40
	v_rcp_f32_e32 v32, v32
	v_rcp_f32_e32 v33, v33
	v_rcp_f32_e32 v34, v34
	v_rcp_f32_e32 v35, v35
	v_rcp_f32_e32 v39, v39

;   DI void operator()(g8::Acc& acc, int pm, int pn, int wr, int wc, int fr, int fq) const {
;     ...
;           if (seg < 2) {
;             if (bj == 0) {
;               const f32x4 c0 = gld<f32x4>(rope, (unsigned)row * 64u), c1 = gld<f32x4>(rope, (unsigned)row * 64u + 16u), s0 = gld<f32x4>(rope, (unsigned)row * 64u + 32u) * sgn, s1 = gld<f32x4>(rope, (unsigned)row * 64u + 48u) * sgn;
;               f32x4 p0, p1;
; #pragma unroll
;               for (int e = 0; e < 4; ++e) { p0[e] = __shfl_xor(o0[e], 16); p1[e] = __shfl_xor(o1[e], 16); }
;               const f32x4 r0 = o0 * c0 + p0 * s0, r1 = o1 * c1 + p1 * s1;
; #pragma unroll
;               for (int e = 0; e < 4; ++e) { o0[e] = use ? r0[e] : o0[e]; o1[e] = use ? r1[e] : o1[e]; }
;             }
;             o0 = o0 * qs; o1 = o1 * qs;
.LBB0_289:
	v_and_b32_e32 v49, 64, v165
	v_xor_b32_e32 v48, 16, v165
	v_add_u32_e32 v49, 64, v49
	v_cmp_lt_i32_e32 vcc, v48, v49
	s_waitcnt vmcnt(2)
	v_pk_mul_f32 v[38:39], v[138:139], v[238:239]
	v_cndmask_b32_e32 v48, v165, v48, vcc
	v_lshlrev_b32_e32 v55, 2, v48
	ds_bpermute_b32 v48, v55, v28
	ds_bpermute_b32 v50, v55, v24
	ds_bpermute_b32 v49, v55, v29
	ds_bpermute_b32 v51, v55, v25
	ds_bpermute_b32 v52, v55, v30
	ds_bpermute_b32 v54, v55, v26
	ds_bpermute_b32 v53, v55, v31
	ds_bpermute_b32 v55, v55, v27
	v_pk_mul_f32 v[46:47], v[138:139], v[246:247]
	v_pk_mul_f32 v[44:45], v[136:137], v[244:245]
	v_pk_mul_f32 v[36:37], v[136:137], v[236:237]
	s_waitcnt lgkmcnt(5)
	v_pk_mul_f32 v[44:45], v[44:45], v[48:49]
	s_waitcnt lgkmcnt(1)
	v_pk_mul_f32 v[46:47], v[46:47], v[52:53]
	v_pk_mul_f32 v[36:37], v[36:37], v[50:51]
	s_waitcnt lgkmcnt(0)
	v_pk_mul_f32 v[38:39], v[38:39], v[54:55]
	v_pk_fma_f32 v[42:43], v[30:31], v[242:243], v[46:47]
	v_pk_fma_f32 v[40:41], v[28:29], v[240:241], v[44:45]
	v_pk_fma_f32 v[34:35], v[26:27], v[234:235], v[38:39]
	v_pk_fma_f32 v[32:33], v[24:25], v[232:233], v[36:37]
	v_cndmask_b32_e64 v29, v29, v41, s[4:5]
	v_cndmask_b32_e64 v28, v28, v40, s[4:5]
	v_cndmask_b32_e64 v31, v31, v43, s[4:5]
	v_cndmask_b32_e64 v30, v30, v42, s[4:5]
	v_cndmask_b32_e64 v25, v25, v33, s[4:5]
	v_cndmask_b32_e64 v24, v24, v32, s[4:5]
	v_cndmask_b32_e64 v27, v27, v35, s[4:5]
	v_cndmask_b32_e64 v26, v26, v34, s[4:5]
	v_mov_b32_e32 v36, v144
	v_mov_b32_e32 v37, v144
	v_pk_mul_f32 v[34:35], v[36:37], v[30:31]
	v_pk_mul_f32 v[32:33], v[144:145], v[28:29]
	v_pk_mul_f32 v[38:39], v[36:37], v[26:27]
	v_pk_mul_f32 v[36:37], v[144:145], v[24:25]

;   DI void operator()(g8::Acc& acc, int pm, int pn, int wr, int wc, int fr, int fq) const {
;     ...
;     if (seg < 5) { dst = slot(p, seg + 1); ld = 1024; cofs = seg * 1024; } else { dst = (bf16_t*)p.out; ld = 2048; cofs = 5 * 1024; }
;     const float qs = (seg == 0) ? 0.125f * LOG2E : 1.0f;
;     const float sgn = (fq == 0) ? -1.0f : 1.0f; const bool use = fq < 2;
;     const unsigned col0 = (unsigned)(pn * BM + wc * 64 - cofs);
; #pragma unroll
;     for (int ai = 0; ai < 2; ++ai)
; #pragma unroll
;       for (int m = 0; m < 4; ++m) {
;         const int row0 = pm * BM + ai * HALF + wr * 64 + m * 16, row = row0 + fr;
;         u32x4 w[2];
; #pragma unroll
;         for (int bj = 0; bj < 2; ++bj) {
;           f32x4 o0 = acc[ai][bj][m][0], o1 = acc[ai][bj][m][1];
;           if (seg < 2) {
;             if (bj == 0) {
;               const f32x4 c0 = gld<f32x4>(rope, (unsigned)row * 64u), c1 = gld<f32x4>(rope, (unsigned)row * 64u + 16u), s0 = gld<f32x4>(rope, (unsigned)row * 64u + 32u) * sgn, s1 = gld<f32x4>(rope, (unsigned)row * 64u + 48u) * sgn;
;               f32x4 p0, p1;
; #pragma unroll
;               for (int e = 0; e < 4; ++e) { p0[e] = __shfl_xor(o0[e], 16); p1[e] = __shfl_xor(o1[e], 16); }
;               const f32x4 r0 = o0 * c0 + p0 * s0, r1 = o1 * c1 + p1 * s1;
; #pragma unroll
;               for (int e = 0; e < 4; ++e) { o0[e] = use ? r0[e] : o0[e]; o1[e] = use ? r1[e] : o1[e]; }
;             }
;             o0 = o0 * qs; o1 = o1 * qs;
;           } else if (seg == 3 || seg == 4) {
; #pragma unroll
;             for (int e = 0; e < 4; ++e) {
;               { const float xx = o0[e], y2 = (-2.0f * 0.7978845608028654f * LOG2E) * (xx + 0.044715f * xx * xx * xx); o0[e] = xx * __builtin_amdgcn_rcpf(1.0f + __builtin_amdgcn_exp2f(y2)); }
;               { const float xx = o1[e], y2 = (-2.0f * 0.7978845608028654f * LOG2E) * (xx + 0.044715f * xx * xx * xx); o1[e] = xx * __builtin_amdgcn_rcpf(1.0f + __builtin_amdgcn_exp2f(y2)); }
;             }
;           } else if (seg >= 5) {
; #pragma unroll
;             for (int e = 0; e < 4; ++e) { o0[e] = __builtin_amdgcn_rcpf(1.0f + __builtin_amdgcn_exp2f(-LOG2E * o0[e])); o1[e] = __builtin_amdgcn_rcpf(1.0f + __builtin_amdgcn_exp2f(-LOG2E * o1[e])); }
;           }
;           w[bj] = pk8(o0, o1);
;         }
;         st_rows16<true>(dst, ld * 2u, (unsigned)row0, col0, fr, fq, w[0], w[1]);
.LBB0_300:
	v_cvt_pk_bf16_f32 v16, v24, v25
	v_mov_b32_e32 v24, 0
	v_cvt_pk_bf16_f32 v17, v32, v33
	v_cvt_pk_bf16_f32 v20, v26, v27
	v_cvt_pk_bf16_f32 v21, v28, v29
	v_cvt_pk_bf16_f32 v22, v30, v31
	v_mov_b32_dpp v24, v16 row_ror:8 row_mask:0xf bank_mask:0xf
	v_mov_b32_e32 v25, 0
	v_mov_b32_e32 v26, 0
	v_mov_b32_e32 v27, 0
	v_cvt_pk_bf16_f32 v18, v34, v35
	v_cvt_pk_bf16_f32 v19, v36, v37
	v_cvt_pk_bf16_f32 v23, v38, v39
	v_mov_b32_dpp v25, v20 row_ror:8 row_mask:0xf bank_mask:0xf
	v_mov_b32_dpp v26, v21 row_ror:8 row_mask:0xf bank_mask:0xf
	v_mov_b32_dpp v27, v22 row_ror:8 row_mask:0xf bank_mask:0xf
	v_cndmask_b32_e64 v16, v17, v24, s[6:7]
	v_cndmask_b32_e64 v20, v24, v17, s[6:7]
	v_or_b32_e32 v24, s20, v158
	v_cndmask_b32_e64 v17, v18, v25, s[6:7]
	v_cndmask_b32_e64 v21, v25, v18, s[6:7]
	v_cndmask_b32_e64 v18, v19, v26, s[6:7]
	v_cndmask_b32_e64 v22, v26, v19, s[6:7]
	v_cndmask_b32_e64 v19, v23, v27, s[6:7]
	v_lshl_add_u32 v25, v24, s19, v147
	s_and_b64 vcc, exec, s[10:11]
	s_cbranch_vccz .Lrope_pf_skip7
	v_add_u32_e32 v248, 0x2c00, v249
	global_load_dwordx4 v[232:235], v248, s[74:75] offset:16
	global_load_dwordx4 v[236:239], v248, s[74:75] offset:48
	global_load_dwordx4 v[240:243], v248, s[74:75]
	global_load_dwordx4 v[244:247], v248, s[74:75] offset:32
.Lrope_pf_skip7:
	global_store_dwordx4 v25, v[16:19], s[90:91] nt
	v_cndmask_b32_e64 v23, v27, v23, s[6:7]
	s_and_b64 vcc, exec, s[10:11]
	v_or_b32_e32 v16, 8, v24
	v_lshl_add_u32 v16, v16, s19, v146
	s_mov_b64 s[0:1], -1
	global_store_dwordx4 v16, v[20:23], s[90:91] nt
	s_cbranch_vccnz .LBB0_308
	s_and_b64 vcc, exec, s[8:9]
	s_cbranch_vccnz .LBB0_305
	s_andn2_b64 vcc, exec, s[88:89]
	v_mov_b32_e32 v19, v15
	v_mov_b32_e32 v18, v14
	v_mov_b32_e32 v17, v13
	v_mov_b32_e32 v16, v12
	v_mov_b32_e32 v23, v11
	v_mov_b32_e32 v22, v10
	v_mov_b32_e32 v21, v9
	v_mov_b32_e32 v20, v8
	s_cbranch_vccnz .LBB0_304
	v_mul_f32_e32 v17, 0xbfb8aa3b, v8
	v_exp_f32_e32 v17, v17
	v_mul_f32_e32 v18, 0xbfb8aa3b, v13
	v_mul_f32_e32 v19, 0xbfb8aa3b, v9
	v_exp_f32_e32 v18, v18
	v_exp_f32_e32 v19, v19
	v_add_f32_e32 v17, 1.0, v17
	v_rcp_f32_e32 v20, v17
	v_add_f32_e32 v17, 1.0, v18
	v_add_f32_e32 v18, 1.0, v19
	v_mul_f32_e32 v19, 0xbfb8aa3b, v14
	v_mul_f32_e32 v21, 0xbfb8aa3b, v10
	v_exp_f32_e32 v19, v19
	v_exp_f32_e32 v22, v21
	v_rcp_f32_e32 v21, v18
	v_mul_f32_e32 v16, 0xbfb8aa3b, v12
	v_add_f32_e32 v18, 1.0, v19
	v_add_f32_e32 v19, 1.0, v22
	v_mul_f32_e32 v22, 0xbfb8aa3b, v15
	v_exp_f32_e32 v23, v22
	v_mul_f32_e32 v22, 0xbfb8aa3b, v11
	v_exp_f32_e32 v16, v16
	v_exp_f32_e32 v24, v22
	v_rcp_f32_e32 v22, v19
	v_add_f32_e32 v19, 1.0, v23
	v_add_f32_e32 v16, 1.0, v16
	v_add_f32_e32 v23, 1.0, v24
	v_rcp_f32_e32 v16, v16
	v_rcp_f32_e32 v17, v17
	v_rcp_f32_e32 v18, v18
	v_rcp_f32_e32 v19, v19
	v_rcp_f32_e32 v23, v23

;   DI void operator()(g8::Acc& acc, int pm, int pn, int wr, int wc, int fr, int fq) const {
;     ...
;           if (seg < 2) {
;             if (bj == 0) {
;               const f32x4 c0 = gld<f32x4>(rope, (unsigned)row * 64u), c1 = gld<f32x4>(rope, (unsigned)row * 64u + 16u), s0 = gld<f32x4>(rope, (unsigned)row * 64u + 32u) * sgn, s1 = gld<f32x4>(rope, (unsigned)row * 64u + 48u) * sgn;
;               f32x4 p0, p1;
; #pragma unroll
;               for (int e = 0; e < 4; ++e) { p0[e] = __shfl_xor(o0[e], 16); p1[e] = __shfl_xor(o1[e], 16); }
;               const f32x4 r0 = o0 * c0 + p0 * s0, r1 = o1 * c1 + p1 * s1;
; #pragma unroll
;               for (int e = 0; e < 4; ++e) { o0[e] = use ? r0[e] : o0[e]; o1[e] = use ? r1[e] : o1[e]; }
;             }
;             o0 = o0 * qs; o1 = o1 * qs;
.LBB0_309:
	v_and_b32_e32 v33, 64, v165
	v_xor_b32_e32 v32, 16, v165
	v_add_u32_e32 v33, 64, v33
	v_cmp_lt_i32_e32 vcc, v32, v33
	s_waitcnt vmcnt(2)
	v_pk_mul_f32 v[22:23], v[138:139], v[238:239]
	v_cndmask_b32_e32 v32, v165, v32, vcc
	v_lshlrev_b32_e32 v39, 2, v32
	ds_bpermute_b32 v32, v39, v12
	ds_bpermute_b32 v34, v39, v8
	ds_bpermute_b32 v33, v39, v13
	ds_bpermute_b32 v35, v39, v9
	ds_bpermute_b32 v36, v39, v14
	ds_bpermute_b32 v38, v39, v10
	ds_bpermute_b32 v37, v39, v15
	ds_bpermute_b32 v39, v39, v11
	v_pk_mul_f32 v[30:31], v[138:139], v[246:247]
	v_pk_mul_f32 v[28:29], v[136:137], v[244:245]
	v_pk_mul_f32 v[20:21], v[136:137], v[236:237]
	s_waitcnt lgkmcnt(5)
	v_pk_mul_f32 v[28:29], v[28:29], v[32:33]
	s_waitcnt lgkmcnt(1)
	v_pk_mul_f32 v[30:31], v[30:31], v[36:37]
	v_pk_mul_f32 v[20:21], v[20:21], v[34:35]
	s_waitcnt lgkmcnt(0)
	v_pk_mul_f32 v[22:23], v[22:23], v[38:39]
	v_pk_fma_f32 v[26:27], v[14:15], v[242:243], v[30:31]
	v_pk_fma_f32 v[24:25], v[12:13], v[240:241], v[28:29]
	v_pk_fma_f32 v[18:19], v[10:11], v[234:235], v[22:23]
	v_pk_fma_f32 v[16:17], v[8:9], v[232:233], v[20:21]
	v_cndmask_b32_e64 v13, v13, v25, s[4:5]
	v_cndmask_b32_e64 v12, v12, v24, s[4:5]
	v_cndmask_b32_e64 v15, v15, v27, s[4:5]
	v_cndmask_b32_e64 v14, v14, v26, s[4:5]
	v_cndmask_b32_e64 v9, v9, v17, s[4:5]
	v_cndmask_b32_e64 v8, v8, v16, s[4:5]
	v_cndmask_b32_e64 v11, v11, v19, s[4:5]
	v_cndmask_b32_e64 v10, v10, v18, s[4:5]
	v_mov_b32_e32 v20, v144
	v_mov_b32_e32 v21, v144
	v_pk_mul_f32 v[18:19], v[20:21], v[14:15]
	v_pk_mul_f32 v[16:17], v[144:145], v[12:13]
	v_pk_mul_f32 v[22:23], v[20:21], v[10:11]
	v_pk_mul_f32 v[20:21], v[144:145], v[8:9]
